# attention row-max chain: the 7 s_nop 0 between independent v_max3 ops removed, on the scalar-add + load-segment priority version
# baseline (speedup 1.0000x reference)
.LBB0_1797:
	s_bitcmp1_b32 s10, 0
	s_cselect_b32 s10, 0x5800, 0
	s_add_i32 s56, s10, 0
	v_add3_u32 v0, s56, v204, v205
	ds_read_b128 v[50:53], v0
	ds_read_b128 v[178:181], v0 offset:32
	ds_read_b128 v[182:185], v0 offset:6656
	ds_read_b128 v[186:189], v0 offset:6688
	s_waitcnt lgkmcnt(3)
	v_mfma_f32_32x32x16_bf16 v[66:81], v[50:53], v[82:85], v[34:49]
	s_waitcnt lgkmcnt(1)
	v_mfma_f32_32x32x16_bf16 v[50:65], v[182:185], v[82:85], v[34:49]
	v_mfma_f32_32x32x16_bf16 v[66:81], v[178:181], v[86:89], v[66:81]
	ds_read_b128 v[178:181], v0 offset:64
	ds_read_b128 v[182:185], v0 offset:96
	s_waitcnt lgkmcnt(2)
	v_mfma_f32_32x32x16_bf16 v[50:65], v[186:189], v[86:89], v[50:65]
	s_waitcnt lgkmcnt(1)
	v_mfma_f32_32x32x16_bf16 v[66:81], v[178:181], v[90:93], v[66:81]
	ds_read_b128 v[178:181], v0 offset:6720
	ds_read_b128 v[186:189], v0 offset:6752
	s_waitcnt lgkmcnt(1)
	v_mfma_f32_32x32x16_bf16 v[50:65], v[178:181], v[90:93], v[50:65]
	v_mfma_f32_32x32x16_bf16 v[66:81], v[182:185], v[94:97], v[66:81]
	ds_read_b128 v[178:181], v0 offset:128
	ds_read_b128 v[182:185], v0 offset:160
	s_waitcnt lgkmcnt(2)
	v_mfma_f32_32x32x16_bf16 v[50:65], v[186:189], v[94:97], v[50:65]
	s_waitcnt lgkmcnt(1)
	v_mfma_f32_32x32x16_bf16 v[66:81], v[178:181], v[98:101], v[66:81]
	ds_read_b128 v[178:181], v0 offset:6784
	ds_read_b128 v[186:189], v0 offset:6816
	s_waitcnt lgkmcnt(1)
	v_mfma_f32_32x32x16_bf16 v[50:65], v[178:181], v[98:101], v[50:65]
	v_mfma_f32_32x32x16_bf16 v[66:81], v[182:185], v[102:105], v[66:81]
	s_waitcnt lgkmcnt(0)
	v_mfma_f32_32x32x16_bf16 v[50:65], v[186:189], v[102:105], v[50:65]
	s_nop 15
	s_nop 7
	s_nop 0
	v_max3_f32 v0, v66, v67, v50
	v_max3_f32 v178, v68, v69, v51
	v_max3_f32 v0, v0, v52, v53
	v_max3_f32 v178, v178, v72, v73
	v_max3_f32 v0, v0, v70, v71
	v_max3_f32 v178, v178, v56, v57
	v_max3_f32 v0, v0, v54, v55
	v_max3_f32 v178, v178, v76, v77
	v_max3_f32 v0, v0, v74, v75
	v_max3_f32 v178, v178, v60, v61
	v_max3_f32 v0, v0, v58, v59
	v_max3_f32 v178, v178, v80, v81
	v_max3_f32 v0, v0, v78, v79
	v_max3_f32 v178, v178, v64, v65
	v_max3_f32 v0, v0, v62, v63
	v_max_f32_e32 v0, v0, v178
	ds_bpermute_b32 v178, v206, v0
	s_waitcnt lgkmcnt(0)
	v_max_f32_e32 v0, v0, v178
	v_cmp_lt_f32_e32 vcc, 0x41000000, v0
	s_cbranch_vccz .LBB0_1801
	v_max_f32_e32 v0, v0, v0
	v_max_f32_e32 v0, 0, v0
	v_exp_f32_e64 v225, -v0
	s_and_saveexec_b64 s[10:11], s[6:7]
	ds_write_b32 v207, v225 offset:45056
	s_or_b64 exec, exec, s[10:11]
	v_add_f32_e32 v173, v173, v0
	v_pk_add_f32 v[66:67], v[66:67], v[0:1] op_sel_hi:[1,0] neg_lo:[0,1] neg_hi:[0,1]
	v_pk_add_f32 v[50:51], v[50:51], v[0:1] op_sel_hi:[1,0] neg_lo:[0,1] neg_hi:[0,1]
	v_pk_add_f32 v[68:69], v[68:69], v[0:1] op_sel_hi:[1,0] neg_lo:[0,1] neg_hi:[0,1]
	v_pk_add_f32 v[52:53], v[52:53], v[0:1] op_sel_hi:[1,0] neg_lo:[0,1] neg_hi:[0,1]
	v_pk_add_f32 v[70:71], v[70:71], v[0:1] op_sel_hi:[1,0] neg_lo:[0,1] neg_hi:[0,1]
	v_pk_add_f32 v[54:55], v[54:55], v[0:1] op_sel_hi:[1,0] neg_lo:[0,1] neg_hi:[0,1]
	v_pk_add_f32 v[72:73], v[72:73], v[0:1] op_sel_hi:[1,0] neg_lo:[0,1] neg_hi:[0,1]
	v_pk_add_f32 v[56:57], v[56:57], v[0:1] op_sel_hi:[1,0] neg_lo:[0,1] neg_hi:[0,1]
	v_pk_add_f32 v[74:75], v[74:75], v[0:1] op_sel_hi:[1,0] neg_lo:[0,1] neg_hi:[0,1]
	v_pk_add_f32 v[58:59], v[58:59], v[0:1] op_sel_hi:[1,0] neg_lo:[0,1] neg_hi:[0,1]
	v_pk_add_f32 v[76:77], v[76:77], v[0:1] op_sel_hi:[1,0] neg_lo:[0,1] neg_hi:[0,1]
	v_pk_add_f32 v[60:61], v[60:61], v[0:1] op_sel_hi:[1,0] neg_lo:[0,1] neg_hi:[0,1]
	v_pk_add_f32 v[78:79], v[78:79], v[0:1] op_sel_hi:[1,0] neg_lo:[0,1] neg_hi:[0,1]
	v_pk_add_f32 v[62:63], v[62:63], v[0:1] op_sel_hi:[1,0] neg_lo:[0,1] neg_hi:[0,1]
	v_pk_add_f32 v[80:81], v[80:81], v[0:1] op_sel_hi:[1,0] neg_lo:[0,1] neg_hi:[0,1]
	v_pk_add_f32 v[64:65], v[64:65], v[0:1] op_sel_hi:[1,0] neg_lo:[0,1] neg_hi:[0,1]
	s_waitcnt lgkmcnt(0)
	v_add_u32_e32 v0, s50, v205
	ds_read_b128 v[178:181], v0 offset:45120
	ds_read_b128 v[182:185], v0 offset:45152
	ds_read_b128 v[186:189], v0 offset:45056
	ds_read_b128 v[190:193], v0 offset:45088
	v_xor_b32_e32 v34, 0x80000000, v173
	v_mov_b32_e32 v35, v34
	v_mov_b32_e32 v36, v34
	v_mov_b32_e32 v37, v34
	v_mov_b32_e32 v38, v34
	v_mov_b32_e32 v39, v34
	v_mov_b32_e32 v40, v34
	v_mov_b32_e32 v41, v34
	v_mov_b32_e32 v42, v34
	v_mov_b32_e32 v43, v34
	v_mov_b32_e32 v44, v34
	v_mov_b32_e32 v45, v34
	v_mov_b32_e32 v46, v34
	v_mov_b32_e32 v47, v34
	v_mov_b32_e32 v48, v34
	v_mov_b32_e32 v49, v34
	v_mul_f32_e32 v224, v224, v225
	s_waitcnt lgkmcnt(2)
	v_pk_mul_f32 v[30:31], v[30:31], v[182:183]
	v_pk_mul_f32 v[26:27], v[26:27], v[178:179]
	s_waitcnt lgkmcnt(0)
	v_pk_mul_f32 v[22:23], v[22:23], v[190:191]
	v_pk_mul_f32 v[32:33], v[32:33], v[184:185]
	v_pk_mul_f32 v[28:29], v[28:29], v[180:181]
	v_pk_mul_f32 v[24:25], v[24:25], v[192:193]
	v_pk_mul_f32 v[20:21], v[20:21], v[188:189]
	v_pk_mul_f32 v[18:19], v[18:19], v[186:187]
	v_pk_mul_f32 v[14:15], v[14:15], v[182:183]
	v_pk_mul_f32 v[10:11], v[10:11], v[178:179]
	v_pk_mul_f32 v[6:7], v[6:7], v[190:191]
	v_pk_mul_f32 v[16:17], v[16:17], v[184:185]
	v_pk_mul_f32 v[12:13], v[12:13], v[180:181]
	v_pk_mul_f32 v[8:9], v[8:9], v[192:193]
	v_pk_mul_f32 v[4:5], v[4:5], v[188:189]
	v_pk_mul_f32 v[2:3], v[2:3], v[186:187]
